# grid barriers: acquire-side buffer_inv issued when the wait starts (before the first generation poll; leaders: with the release write-back) instead of after the release is observed
# speedup vs baseline: 1.0070x; 1.0070x over previous
; __device__ __forceinline__ unsigned xb_ld(unsigned* p)              { return __hip_atomic_load(p, __ATOMIC_RELAXED, __HIP_MEMORY_SCOPE_AGENT); }
; __device__ __forceinline__ unsigned xb_add(unsigned* p, unsigned v) { return __hip_atomic_fetch_add(p, v, __ATOMIC_RELAXED, __HIP_MEMORY_SCOPE_AGENT); }
; #define XB_SPIN(cond, bar) do { unsigned _sp = 0; while (cond) { __builtin_amdgcn_s_sleep(1); \
;     if ((++_sp & 255u) == 0u) { if (xb_ld(&(bar)[XB_TMO])) break; if (_sp > XB_SPIN_CAP) { atomicAdd(&(bar)[XB_TMO], 1u); break; } } } } while (0)
; __device__ __forceinline__ void xcd_barrier(const XcdBarrier& b) {
;     ...
;         const unsigned old = xb_add(&bar[XB_XSUB(b.x)], 1u);
;         const unsigned gen = old / nloc;
;         if (old + 1u == (gen + 1u) * nloc) {
;             __builtin_amdgcn_fence(__ATOMIC_RELEASE, "agent");
;             asm volatile("s_waitcnt vmcnt(0)" ::: "memory");
;             const unsigned og = xb_add(&bar[XB_TOP], 1u);
;             const unsigned tg = og / nx;
;             if (og + 1u == (tg + 1u) * nx) xb_add(&bar[XB_TOPGEN], 1u);
;             else XB_SPIN(xb_ld(&bar[XB_TOPGEN]) == tg, bar);
;             __builtin_amdgcn_fence(__ATOMIC_ACQUIRE, "agent");
;             xb_add(&bar[XB_XGEN(b.x)], 1u);
;             asm volatile("s_waitcnt vmcnt(0)" ::: "memory");
;         } else {
;             XB_SPIN(xb_ld(&bar[XB_XGEN(b.x)]) == gen, bar);
.LBB0_88:
	s_or_b64 exec, exec, s[8:9]
	v_cvt_f32_u32_e32 v4, v2
	s_waitcnt vmcnt(0)
	v_readfirstlane_b32 s6, v3
	v_sub_u32_e32 v3, 0, v2
	v_rcp_iflag_f32_e32 v4, v4
	v_add_u32_e32 v5, s6, v1
	v_mul_f32_e32 v4, 0x4f7ffffe, v4
	v_cvt_u32_f32_e32 v4, v4
	v_mul_lo_u32 v1, v3, v4
	v_mul_hi_u32 v1, v4, v1
	v_add_u32_e32 v1, v4, v1
	v_mul_hi_u32 v1, v5, v1
	v_mul_lo_u32 v3, v1, v2
	v_sub_u32_e32 v3, v5, v3
	v_add_u32_e32 v4, 1, v1
	v_cmp_ge_u32_e32 vcc, v3, v2
	s_nop 1
	v_cndmask_b32_e32 v1, v1, v4, vcc
	v_sub_u32_e32 v4, v3, v2
	v_cndmask_b32_e32 v3, v3, v4, vcc
	v_add_u32_e32 v4, 1, v1
	v_cmp_ge_u32_e32 vcc, v3, v2
	v_add_u32_e32 v3, 1, v5
	s_nop 0
	v_cndmask_b32_e32 v1, v1, v4, vcc
	v_mul_lo_u32 v4, v2, v1
	v_add_u32_e32 v2, v4, v2
	v_cmp_ne_u32_e32 vcc, v3, v2
	s_and_saveexec_b64 s[6:7], vcc
	s_xor_b64 s[6:7], exec, s[6:7]
	s_cbranch_execz .LBB0_102
	s_waitcnt lgkmcnt(0)
	v_mov_b32_e32 v0, 0x2000
	buffer_inv sc1
	global_load_dword v0, v0, s[4:5] offset:1024 sc1
	s_add_u32 s12, s4, 0x2400
	s_addc_u32 s13, s5, 0
	s_waitcnt vmcnt(0)
	v_cmp_eq_u32_e32 vcc, v0, v1
	s_and_saveexec_b64 s[8:9], vcc
	s_cbranch_execz .LBB0_101
	s_add_u32 s10, s96, 0x180200
	s_addc_u32 s11, s97, 0
	s_mov_b32 s24, 1
	s_mov_b64 s[14:15], 0
	v_mov_b32_e32 v0, 0
	s_branch .LBB0_92

; __device__ __forceinline__ unsigned xb_ld(unsigned* p)              { return __hip_atomic_load(p, __ATOMIC_RELAXED, __HIP_MEMORY_SCOPE_AGENT); }
; __device__ __forceinline__ unsigned xb_add(unsigned* p, unsigned v) { return __hip_atomic_fetch_add(p, v, __ATOMIC_RELAXED, __HIP_MEMORY_SCOPE_AGENT); }
; #define XB_SPIN(cond, bar) do { unsigned _sp = 0; while (cond) { __builtin_amdgcn_s_sleep(1); \
;     if ((++_sp & 255u) == 0u) { if (xb_ld(&(bar)[XB_TMO])) break; if (_sp > XB_SPIN_CAP) { atomicAdd(&(bar)[XB_TMO], 1u); break; } } } } while (0)
; __device__ __forceinline__ void xcd_barrier(const XcdBarrier& b) {
;     ...
;             __builtin_amdgcn_fence(__ATOMIC_RELEASE, "agent");
;             asm volatile("s_waitcnt vmcnt(0)" ::: "memory");
;             const unsigned og = xb_add(&bar[XB_TOP], 1u);
;             const unsigned tg = og / nx;
;             if (og + 1u == (tg + 1u) * nx) xb_add(&bar[XB_TOPGEN], 1u);
;             else XB_SPIN(xb_ld(&bar[XB_TOPGEN]) == tg, bar);
;             __builtin_amdgcn_fence(__ATOMIC_ACQUIRE, "agent");
;             xb_add(&bar[XB_XGEN(b.x)], 1u);
;             asm volatile("s_waitcnt vmcnt(0)" ::: "memory");
;         } else {
;             XB_SPIN(xb_ld(&bar[XB_XGEN(b.x)]) == gen, bar);
;             __builtin_amdgcn_fence(__ATOMIC_ACQUIRE, "agent");
.LBB0_101:
	s_or_b64 exec, exec, s[8:9]
	s_waitcnt vmcnt(0)
	s_waitcnt vmcnt(0)
.LBB0_102:
	s_andn2_saveexec_b64 s[6:7], s[6:7]
	s_cbranch_execz .LBB0_122
	s_mov_b64 s[6:7], exec
	buffer_wbl2 sc1
	buffer_inv sc1
	s_waitcnt lgkmcnt(0)
	s_waitcnt vmcnt(0)
	v_mbcnt_lo_u32_b32 v1, s6, 0
	v_mbcnt_hi_u32_b32 v1, s7, v1
	v_cmp_eq_u32_e32 vcc, 0, v1
	s_and_saveexec_b64 s[8:9], vcc
	s_cbranch_execz .LBB0_105
	s_bcnt1_i32_b64 s6, s[6:7]
	v_mov_b32_e32 v2, 0x183000
	v_mov_b32_e32 v3, s6
	global_atomic_add v2, v2, v3, s[96:97] offset:1024 sc0

; __device__ __forceinline__ unsigned xb_ld(unsigned* p)              { return __hip_atomic_load(p, __ATOMIC_RELAXED, __HIP_MEMORY_SCOPE_AGENT); }
; __device__ __forceinline__ unsigned xb_add(unsigned* p, unsigned v) { return __hip_atomic_fetch_add(p, v, __ATOMIC_RELAXED, __HIP_MEMORY_SCOPE_AGENT); }
; #define XB_SPIN(cond, bar) do { unsigned _sp = 0; while (cond) { __builtin_amdgcn_s_sleep(1); \
;     if ((++_sp & 255u) == 0u) { if (xb_ld(&(bar)[XB_TMO])) break; if (_sp > XB_SPIN_CAP) { atomicAdd(&(bar)[XB_TMO], 1u); break; } } } } while (0)
; __device__ __forceinline__ void xcd_barrier(const XcdBarrier& b) {
;     ...
;             const unsigned tg = og / nx;
;             if (og + 1u == (tg + 1u) * nx) xb_add(&bar[XB_TOPGEN], 1u);
;             else XB_SPIN(xb_ld(&bar[XB_TOPGEN]) == tg, bar);
;             __builtin_amdgcn_fence(__ATOMIC_ACQUIRE, "agent");
;             xb_add(&bar[XB_XGEN(b.x)], 1u);
.LBB0_119:
	s_or_b64 exec, exec, s[6:7]
	s_mov_b64 s[6:7], exec
	v_mbcnt_lo_u32_b32 v0, s6, 0
	v_mbcnt_hi_u32_b32 v0, s7, v0
	v_cmp_eq_u32_e32 vcc, 0, v0
	s_waitcnt vmcnt(0)
	s_and_saveexec_b64 s[8:9], vcc
	s_cbranch_execz .LBB0_121
	s_bcnt1_i32_b64 s6, s[6:7]
	v_mov_b32_e32 v0, 0x2000
	v_mov_b32_e32 v1, s6
	global_atomic_add v0, v1, s[4:5] offset:1024

; __device__ __forceinline__ unsigned xb_ld(unsigned* p)              { return __hip_atomic_load(p, __ATOMIC_RELAXED, __HIP_MEMORY_SCOPE_AGENT); }
; __device__ __forceinline__ unsigned xb_add(unsigned* p, unsigned v) { return __hip_atomic_fetch_add(p, v, __ATOMIC_RELAXED, __HIP_MEMORY_SCOPE_AGENT); }
; #define XB_SPIN(cond, bar) do { unsigned _sp = 0; while (cond) { __builtin_amdgcn_s_sleep(1); \
;     if ((++_sp & 255u) == 0u) { if (xb_ld(&(bar)[XB_TMO])) break; if (_sp > XB_SPIN_CAP) { atomicAdd(&(bar)[XB_TMO], 1u); break; } } } } while (0)
; __device__ __forceinline__ void xcd_barrier(const XcdBarrier& b) {
;     ...
;         const unsigned old = xb_add(&bar[XB_XSUB(b.x)], 1u);
;         const unsigned gen = old / nloc;
;         if (old + 1u == (gen + 1u) * nloc) {
;             __builtin_amdgcn_fence(__ATOMIC_RELEASE, "agent");
;             asm volatile("s_waitcnt vmcnt(0)" ::: "memory");
;             const unsigned og = xb_add(&bar[XB_TOP], 1u);
;             const unsigned tg = og / nx;
;             if (og + 1u == (tg + 1u) * nx) xb_add(&bar[XB_TOPGEN], 1u);
;             else XB_SPIN(xb_ld(&bar[XB_TOPGEN]) == tg, bar);
;             __builtin_amdgcn_fence(__ATOMIC_ACQUIRE, "agent");
;             xb_add(&bar[XB_XGEN(b.x)], 1u);
;             asm volatile("s_waitcnt vmcnt(0)" ::: "memory");
;         } else {
;             XB_SPIN(xb_ld(&bar[XB_XGEN(b.x)]) == gen, bar);
.LBB0_191:
	s_or_b64 exec, exec, s[6:7]
	v_cvt_f32_u32_e32 v4, v2
	s_waitcnt vmcnt(0)
	v_readfirstlane_b32 s4, v3
	v_sub_u32_e32 v3, 0, v2
	v_rcp_iflag_f32_e32 v4, v4
	v_add_u32_e32 v5, s4, v1
	v_mul_f32_e32 v4, 0x4f7ffffe, v4
	v_cvt_u32_f32_e32 v4, v4
	v_mul_lo_u32 v1, v3, v4
	v_mul_hi_u32 v1, v4, v1
	v_add_u32_e32 v1, v4, v1
	v_mul_hi_u32 v1, v5, v1
	v_mul_lo_u32 v3, v1, v2
	v_sub_u32_e32 v3, v5, v3
	v_add_u32_e32 v4, 1, v1
	v_cmp_ge_u32_e32 vcc, v3, v2
	s_nop 1
	v_cndmask_b32_e32 v1, v1, v4, vcc
	v_sub_u32_e32 v4, v3, v2
	v_cndmask_b32_e32 v3, v3, v4, vcc
	v_add_u32_e32 v4, 1, v1
	v_cmp_ge_u32_e32 vcc, v3, v2
	v_add_u32_e32 v3, 1, v5
	s_nop 0
	v_cndmask_b32_e32 v1, v1, v4, vcc
	v_mul_lo_u32 v4, v2, v1
	v_add_u32_e32 v2, v4, v2
	v_cmp_ne_u32_e32 vcc, v3, v2
	s_and_saveexec_b64 s[4:5], vcc
	s_xor_b64 s[4:5], exec, s[4:5]
	s_cbranch_execz .LBB0_205
	s_waitcnt lgkmcnt(0)
	v_mov_b32_e32 v0, 0x2000
	buffer_inv sc1
	global_load_dword v0, v0, s[2:3] offset:1024 sc1
	s_add_u32 s10, s2, 0x2400
	s_addc_u32 s11, s3, 0
	s_waitcnt vmcnt(0)
	v_cmp_eq_u32_e32 vcc, v0, v1
	s_and_saveexec_b64 s[6:7], vcc
	s_cbranch_execz .LBB0_204
	s_add_u32 s8, s96, 0x180200
	s_addc_u32 s9, s97, 0
	s_mov_b32 s22, 1
	s_mov_b64 s[12:13], 0
	v_mov_b32_e32 v0, 0
	s_branch .LBB0_195

; __device__ __forceinline__ unsigned xb_ld(unsigned* p)              { return __hip_atomic_load(p, __ATOMIC_RELAXED, __HIP_MEMORY_SCOPE_AGENT); }
; __device__ __forceinline__ unsigned xb_add(unsigned* p, unsigned v) { return __hip_atomic_fetch_add(p, v, __ATOMIC_RELAXED, __HIP_MEMORY_SCOPE_AGENT); }
; #define XB_SPIN(cond, bar) do { unsigned _sp = 0; while (cond) { __builtin_amdgcn_s_sleep(1); \
;     if ((++_sp & 255u) == 0u) { if (xb_ld(&(bar)[XB_TMO])) break; if (_sp > XB_SPIN_CAP) { atomicAdd(&(bar)[XB_TMO], 1u); break; } } } } while (0)
; __device__ __forceinline__ void xcd_barrier(const XcdBarrier& b) {
;     ...
;             __builtin_amdgcn_fence(__ATOMIC_RELEASE, "agent");
;             asm volatile("s_waitcnt vmcnt(0)" ::: "memory");
;             const unsigned og = xb_add(&bar[XB_TOP], 1u);
;             const unsigned tg = og / nx;
;             if (og + 1u == (tg + 1u) * nx) xb_add(&bar[XB_TOPGEN], 1u);
;             else XB_SPIN(xb_ld(&bar[XB_TOPGEN]) == tg, bar);
;             __builtin_amdgcn_fence(__ATOMIC_ACQUIRE, "agent");
;             xb_add(&bar[XB_XGEN(b.x)], 1u);
;             asm volatile("s_waitcnt vmcnt(0)" ::: "memory");
;         } else {
;             XB_SPIN(xb_ld(&bar[XB_XGEN(b.x)]) == gen, bar);
;             __builtin_amdgcn_fence(__ATOMIC_ACQUIRE, "agent");
.LBB0_204:
	s_or_b64 exec, exec, s[6:7]
	s_waitcnt vmcnt(0)
	s_waitcnt vmcnt(0)
.LBB0_205:
	s_andn2_saveexec_b64 s[4:5], s[4:5]
	s_cbranch_execz .LBB0_225
	s_mov_b64 s[4:5], exec
	buffer_wbl2 sc1
	buffer_inv sc1
	s_waitcnt lgkmcnt(0)
	s_waitcnt vmcnt(0)
	v_mbcnt_lo_u32_b32 v1, s4, 0
	v_mbcnt_hi_u32_b32 v1, s5, v1
	v_cmp_eq_u32_e32 vcc, 0, v1
	s_and_saveexec_b64 s[6:7], vcc
	s_cbranch_execz .LBB0_208
	s_bcnt1_i32_b64 s4, s[4:5]
	v_mov_b32_e32 v2, 0x183000
	v_mov_b32_e32 v3, s4
	global_atomic_add v2, v2, v3, s[96:97] offset:1024 sc0

; __device__ __forceinline__ unsigned xb_ld(unsigned* p)              { return __hip_atomic_load(p, __ATOMIC_RELAXED, __HIP_MEMORY_SCOPE_AGENT); }
; __device__ __forceinline__ unsigned xb_add(unsigned* p, unsigned v) { return __hip_atomic_fetch_add(p, v, __ATOMIC_RELAXED, __HIP_MEMORY_SCOPE_AGENT); }
; #define XB_SPIN(cond, bar) do { unsigned _sp = 0; while (cond) { __builtin_amdgcn_s_sleep(1); \
;     if ((++_sp & 255u) == 0u) { if (xb_ld(&(bar)[XB_TMO])) break; if (_sp > XB_SPIN_CAP) { atomicAdd(&(bar)[XB_TMO], 1u); break; } } } } while (0)
; __device__ __forceinline__ void xcd_barrier(const XcdBarrier& b) {
;     ...
;             const unsigned tg = og / nx;
;             if (og + 1u == (tg + 1u) * nx) xb_add(&bar[XB_TOPGEN], 1u);
;             else XB_SPIN(xb_ld(&bar[XB_TOPGEN]) == tg, bar);
;             __builtin_amdgcn_fence(__ATOMIC_ACQUIRE, "agent");
;             xb_add(&bar[XB_XGEN(b.x)], 1u);
.LBB0_222:
	s_or_b64 exec, exec, s[4:5]
	s_mov_b64 s[4:5], exec
	v_mbcnt_lo_u32_b32 v0, s4, 0
	v_mbcnt_hi_u32_b32 v0, s5, v0
	v_cmp_eq_u32_e32 vcc, 0, v0
	s_waitcnt vmcnt(0)
	s_and_saveexec_b64 s[6:7], vcc
	s_cbranch_execz .LBB0_224
	s_bcnt1_i32_b64 s4, s[4:5]
	v_mov_b32_e32 v0, 0x2000
	v_mov_b32_e32 v1, s4
	global_atomic_add v0, v1, s[2:3] offset:1024

; __device__ __forceinline__ unsigned xb_ld(unsigned* p)              { return __hip_atomic_load(p, __ATOMIC_RELAXED, __HIP_MEMORY_SCOPE_AGENT); }
; __device__ __forceinline__ unsigned xb_add(unsigned* p, unsigned v) { return __hip_atomic_fetch_add(p, v, __ATOMIC_RELAXED, __HIP_MEMORY_SCOPE_AGENT); }
; #define XB_SPIN(cond, bar) do { unsigned _sp = 0; while (cond) { __builtin_amdgcn_s_sleep(1); \
;     if ((++_sp & 255u) == 0u) { if (xb_ld(&(bar)[XB_TMO])) break; if (_sp > XB_SPIN_CAP) { atomicAdd(&(bar)[XB_TMO], 1u); break; } } } } while (0)
; __device__ __forceinline__ void xcd_barrier(const XcdBarrier& b) {
;     ...
;         const unsigned old = xb_add(&bar[XB_XSUB(b.x)], 1u);
;         const unsigned gen = old / nloc;
;         if (old + 1u == (gen + 1u) * nloc) {
;             __builtin_amdgcn_fence(__ATOMIC_RELEASE, "agent");
;             asm volatile("s_waitcnt vmcnt(0)" ::: "memory");
;             const unsigned og = xb_add(&bar[XB_TOP], 1u);
;             const unsigned tg = og / nx;
;             if (og + 1u == (tg + 1u) * nx) xb_add(&bar[XB_TOPGEN], 1u);
;             else XB_SPIN(xb_ld(&bar[XB_TOPGEN]) == tg, bar);
;             __builtin_amdgcn_fence(__ATOMIC_ACQUIRE, "agent");
;             xb_add(&bar[XB_XGEN(b.x)], 1u);
;             asm volatile("s_waitcnt vmcnt(0)" ::: "memory");
;         } else {
;             XB_SPIN(xb_ld(&bar[XB_XGEN(b.x)]) == gen, bar);
.LBB0_458:
	s_or_b64 exec, exec, s[6:7]
	v_cvt_f32_u32_e32 v4, v2
	s_waitcnt vmcnt(0)
	v_readfirstlane_b32 s4, v3
	v_sub_u32_e32 v3, 0, v2
	v_rcp_iflag_f32_e32 v4, v4
	v_add_u32_e32 v5, s4, v1
	v_mul_f32_e32 v4, 0x4f7ffffe, v4
	v_cvt_u32_f32_e32 v4, v4
	v_mul_lo_u32 v1, v3, v4
	v_mul_hi_u32 v1, v4, v1
	v_add_u32_e32 v1, v4, v1
	v_mul_hi_u32 v1, v5, v1
	v_mul_lo_u32 v3, v1, v2
	v_sub_u32_e32 v3, v5, v3
	v_add_u32_e32 v4, 1, v1
	v_cmp_ge_u32_e32 vcc, v3, v2
	s_nop 1
	v_cndmask_b32_e32 v1, v1, v4, vcc
	v_sub_u32_e32 v4, v3, v2
	v_cndmask_b32_e32 v3, v3, v4, vcc
	v_add_u32_e32 v4, 1, v1
	v_cmp_ge_u32_e32 vcc, v3, v2
	v_add_u32_e32 v3, 1, v5
	s_nop 0
	v_cndmask_b32_e32 v1, v1, v4, vcc
	v_mul_lo_u32 v4, v2, v1
	v_add_u32_e32 v2, v4, v2
	v_cmp_ne_u32_e32 vcc, v3, v2
	s_and_saveexec_b64 s[4:5], vcc
	s_xor_b64 s[4:5], exec, s[4:5]
	s_cbranch_execz .LBB0_472
	s_waitcnt lgkmcnt(0)
	v_mov_b32_e32 v0, 0x2000
	buffer_inv sc1
	global_load_dword v0, v0, s[2:3] offset:1024 sc1
	s_add_u32 s12, s2, 0x2400
	s_addc_u32 s13, s3, 0
	s_waitcnt vmcnt(0)
	v_cmp_eq_u32_e32 vcc, v0, v1
	s_and_saveexec_b64 s[6:7], vcc
	s_cbranch_execz .LBB0_471
	s_add_u32 s8, s96, 0x180200
	s_addc_u32 s9, s97, 0
	s_mov_b32 s24, 1
	s_mov_b64 s[14:15], 0
	v_mov_b32_e32 v0, 0
	s_branch .LBB0_462
